# P4 K fragment-image copy: the four row loads of an item issued together with one wait (was load/wait/store four times in series)
# speedup vs baseline: 1.0064x; 1.0064x over previous
.LBB0_656:
	s_mul_hi_i32 s2, s14, 0x2aaaaaab
	s_lshr_b32 s3, s2, 31
	s_add_i32 s4, s2, s3
	s_mul_i32 s2, s4, -6
	s_add_i32 s17, s14, s2
	s_ashr_i32 s10, s4, 7
	s_and_b32 s16, s4, 0x7f
	s_cmp_lt_i32 s17, 4
	s_mulk_i32 s4, 0xfe80
	s_cselect_b64 s[2:3], -1, 0
	s_add_i32 s15, s12, s4
	s_add_i32 s8, s15, 0xffffff00
	s_cmp_eq_u32 s17, 4
	s_cselect_b64 s[4:5], -1, 0
	s_and_b64 s[6:7], s[4:5], exec
	s_movk_i32 s6, 0x480
	v_mov_b32_e32 v10, v0
	s_cselect_b32 s9, s6, 0x500
	s_and_b64 s[6:7], s[2:3], exec
	s_load_dwordx2 s[6:7], s[0:1], 0x98
	s_cselect_b32 s18, s8, s9
	v_ashrrev_i32_e32 v6, 2, v10
	v_and_b32_e32 v6, -8, v6
	v_ashrrev_i32_e32 v7, 31, v6
	s_waitcnt lgkmcnt(0)
	s_add_u32 s20, s6, 0x5600000
	s_addc_u32 s21, s7, 0
	s_ashr_i32 s11, s10, 31
	s_lshl_b64 s[8:9], s[10:11], 12
	s_lshl_b32 s11, s16, 5
	s_or_b32 s8, s8, s11
	v_and_or_b32 v4, v10, 31, s8
	v_mov_b64_e32 v[2:3], s[20:21]
	v_mad_u64_u32 v[4:5], s[20:21], v4, s64, v[2:3]
	v_mad_i32_i24 v5, s9, v234, v5
	s_ashr_i32 s19, s18, 31
	v_lshl_add_u64 v[4:5], s[18:19], 1, v[4:5]
	s_and_b64 s[18:19], s[4:5], exec
	s_mov_b32 s11, 0x1e000000
	s_cselect_b32 s11, s11, 0x1e800000
	s_and_b64 s[18:19], s[2:3], exec
	s_cselect_b32 s11, 0x1b600000, s11
	s_add_u32 s20, s6, s11
	s_addc_u32 s21, s7, 0
	s_lshl_b32 s11, s10, 2
	s_add_i32 s17, s17, s11
	s_and_b64 s[18:19], s[2:3], exec
	s_cselect_b32 s10, s17, s10
	s_ashr_i32 s11, s10, 31
	s_lshl_b64 s[10:11], s[10:11], 19
	s_add_u32 s17, s20, s10
	s_addc_u32 s19, s21, s11
	s_lshl_b32 s16, s16, 12
	v_lshl_add_u64 v[8:9], v[6:7], 1, v[4:5]
	s_add_u32 s18, s17, s16
	v_lshlrev_b32_e32 v4, 3, v10
	s_addc_u32 s19, s19, 0
	v_ashrrev_i32_e32 v5, 31, v4
	v_lshl_add_u64 v[10:11], v[4:5], 1, s[18:19]
	global_load_dwordx4 v[44:47], v[8:9], off
	global_load_dwordx4 v[48:51], v[8:9], off offset:32
	global_load_dwordx4 v[52:55], v[8:9], off offset:64
	global_load_dwordx4 v[56:59], v[8:9], off offset:96
	v_mov_b32_e32 v18, v0
	s_and_b64 s[18:19], s[4:5], exec
	s_movk_i32 s17, 0x4c0
	s_cselect_b32 s17, s17, 0x540
	s_and_b64 s[18:19], s[2:3], exec
	s_cselect_b32 s92, s15, s17
	s_and_b64 s[4:5], s[4:5], exec
	s_mov_b32 s4, 0x1e400000
	s_cselect_b32 s4, s4, 0x1ec00000
	s_and_b64 s[2:3], s[2:3], exec
	s_cselect_b32 s2, 0x1c600000, s4
	s_add_u32 s2, s6, s2
	s_addc_u32 s3, s7, 0
	s_add_u32 s2, s2, s10
	s_addc_u32 s3, s3, s11
	s_add_u32 s2, s2, s16
	s_addc_u32 s3, s3, 0
	s_add_i32 s14, s14, s68
	s_addk_i32 s14, 0xff00
	s_add_i32 s12, s12, s13
	s_cmpk_gt_i32 s14, 0x17ff
	s_waitcnt vmcnt(0)
	global_store_dwordx4 v[10:11], v[44:47], off
	global_store_dwordx4 v[10:11], v[48:51], off offset:1024
	global_store_dwordx4 v[10:11], v[52:55], off offset:2048
	global_store_dwordx4 v[10:11], v[56:59], off offset:3072
	s_nop 0
	v_and_b32_e32 v19, 31, v18
	v_or_b32_e32 v4, s8, v19
	v_mad_u64_u32 v[2:3], s[18:19], v4, s64, v[2:3]
	v_mad_i32_i24 v3, s9, v234, v3
	v_and_b32_e32 v4, 0xffffffe0, v18
	v_lshl_add_u64 v[2:3], s[92:93], 1, v[2:3]
	v_ashrrev_i32_e32 v5, 31, v4
	v_lshl_add_u64 v[14:15], v[4:5], 1, v[2:3]
	v_mov_b32_e32 v2, s77
	v_mad_u32_u24 v20, v19, s56, v2
	v_lshl_add_u32 v21, v4, 1, v20
	global_load_dwordx4 v[2:5], v[14:15], off offset:48
	global_load_dwordx4 v[6:9], v[14:15], off offset:32
	global_load_dwordx4 v[10:13], v[14:15], off offset:16
	s_nop 0
	global_load_dwordx4 v[14:17], v[14:15], off
	s_waitcnt vmcnt(0)
	ds_write2_b32 v21, v14, v15 offset1:1
	ds_write2_b32 v21, v16, v17 offset0:2 offset1:3
	ds_write2_b32 v21, v10, v11 offset0:4 offset1:5
	ds_write2_b32 v21, v12, v13 offset0:6 offset1:7
	ds_write2_b32 v21, v6, v7 offset0:8 offset1:9
	ds_write2_b32 v21, v8, v9 offset0:10 offset1:11
	ds_write2_b32 v21, v2, v3 offset0:12 offset1:13
	ds_write2_b32 v21, v4, v5 offset0:14 offset1:15
	v_lshlrev_b32_e32 v2, 3, v18
	v_ashrrev_i32_e32 v3, 31, v2
	v_lshl_add_u64 v[6:7], v[2:3], 1, s[2:3]
	v_ashrrev_i32_e32 v3, 3, v18
	v_and_b32_e32 v4, 0x3ffffffc, v3
	v_mad_i32_i24 v2, v19, s58, v20
	v_mad_u64_u32 v[8:9], s[2:3], v4, s56, v[2:3]
	v_or_b32_e32 v3, 3, v3
	s_waitcnt lgkmcnt(0)
	v_mad_u64_u32 v[10:11], s[2:3], v3, s56, v[2:3]
	ds_read_u16 v4, v8
	ds_read_u16 v5, v8 offset:132
	ds_read_u16 v9, v8 offset:264
	ds_read_u16 v3, v10
	ds_read_u16 v11, v8 offset:1056
	ds_read_u16 v12, v8 offset:1188
	ds_read_u16 v13, v8 offset:1320
	ds_read_u16 v14, v10 offset:1056
	s_waitcnt lgkmcnt(6)
	v_lshl_or_b32 v2, v5, 16, v4
	s_waitcnt lgkmcnt(4)
	v_lshl_or_b32 v3, v3, 16, v9
	s_waitcnt lgkmcnt(2)
	v_lshl_or_b32 v4, v12, 16, v11
	s_waitcnt lgkmcnt(0)
	v_lshl_or_b32 v5, v14, 16, v13
	global_store_dwordx4 v[6:7], v[2:5], off
	ds_read_u16 v2, v8 offset:2112
	ds_read_u16 v3, v8 offset:2244
	ds_read_u16 v4, v8 offset:2376
	ds_read_u16 v5, v8 offset:2508
	ds_read_u16 v9, v8 offset:3168
	ds_read_u16 v11, v8 offset:3300
	ds_read_u16 v12, v8 offset:3432
	ds_read_u16 v13, v8 offset:3564
	s_waitcnt lgkmcnt(6)
	v_lshl_or_b32 v2, v3, 16, v2
	s_waitcnt lgkmcnt(4)
	v_lshl_or_b32 v3, v5, 16, v4
	s_waitcnt lgkmcnt(2)
	v_lshl_or_b32 v4, v11, 16, v9
	s_waitcnt lgkmcnt(0)
	v_lshl_or_b32 v5, v13, 16, v12
	global_store_dwordx4 v[6:7], v[2:5], off offset:1024
	ds_read_u16 v2, v8 offset:64
	ds_read_u16 v3, v8 offset:196
	ds_read_u16 v4, v8 offset:328
	ds_read_u16 v5, v10 offset:64
	ds_read_u16 v9, v8 offset:1120
	ds_read_u16 v11, v8 offset:1252
	ds_read_u16 v12, v8 offset:1384
	ds_read_u16 v10, v10 offset:1120
	s_waitcnt lgkmcnt(6)
	v_lshl_or_b32 v2, v3, 16, v2
	s_waitcnt lgkmcnt(4)
	v_lshl_or_b32 v3, v5, 16, v4
	s_waitcnt lgkmcnt(2)
	v_lshl_or_b32 v4, v11, 16, v9
	s_waitcnt lgkmcnt(0)
	v_lshl_or_b32 v5, v10, 16, v12
	global_store_dwordx4 v[6:7], v[2:5], off offset:2048
	ds_read_u16 v2, v8 offset:2176
	ds_read_u16 v3, v8 offset:2308
	ds_read_u16 v4, v8 offset:2440
	ds_read_u16 v5, v8 offset:2572
	ds_read_u16 v9, v8 offset:3232
	ds_read_u16 v10, v8 offset:3364
	ds_read_u16 v11, v8 offset:3496
	ds_read_u16 v8, v8 offset:3628
	s_waitcnt lgkmcnt(6)
	v_lshl_or_b32 v2, v3, 16, v2
	s_waitcnt lgkmcnt(4)
	v_lshl_or_b32 v3, v5, 16, v4
	s_waitcnt lgkmcnt(2)
	v_lshl_or_b32 v4, v10, 16, v9
	s_waitcnt lgkmcnt(0)
	v_lshl_or_b32 v5, v8, 16, v11
	global_store_dwordx4 v[6:7], v[2:5], off offset:3072
	s_waitcnt lgkmcnt(0)
	s_cbranch_scc0 .LBB0_656
